# fixed carry bug (s_addc separated from s_add by an SCC writer) in steady-loop DMA address setup; 3x-unrolled steady attention loops with constant ring offsets
# speedup vs baseline: 1.0251x; 1.0109x over previous
; #define ATT_EVEN(j_, k2_, v1_) do { if (!F32) { if ((j_) + 2 < nt) ATT_DMAK((j_) + 2, k2_); if ((j_) + 1 < nt) ATT_DMAV((j_) + 1, v1_); } } while (0)
; template <bool F32>
; __device__ __forceinline__ void attn_unit(const AUnit& U, LAS unsigned char* lds, float lam, const float* subg) {
;     ...
; #pragma unroll 1
;         for (int it = 0; it <= nt; ++it) {
;             ATT_EVEN(it, r0, r2);
;             if (it >= 1 && it <= mnt) ATT_SM(it - 1);
;             ATT_MM((it >= 1 && it <= mnt), (it < mnt), r0, r1);
.LBB0_704:
	s_cmp_lg_u32 s95, 1
	s_cbranch_scc1 .Lc1_gen
	s_cmp_lg_u32 s24, 0
	s_cbranch_scc1 .Lc1_gen
	s_min_i32 s30, s85, s87
	s_cmp_ge_i32 s95, s30
	s_cbranch_scc1 .Lc1_gen
	s_andn2_b64 vcc, exec, s[4:5]
	s_cbranch_vccz .Lc1_steady

; #define ATT_BASEPRIO_EARLY() do { if (comp) __builtin_amdgcn_s_setprio(1); } while (0)
; template <bool F32>
; __device__ __forceinline__ void attn_unit(const AUnit& U, LAS unsigned char* lds, float lam, const float* subg) {
;     ...
;     const int mnt = active ? my_nt : 0;
;     ATT_BASEPRIO_EARLY();
;     bf16x8 pa[4];
; #pragma unroll
;     for (int k = 0; k < 4; ++k) pa[k] = (bf16x8){0, 0, 0, 0, 0, 0, 0, 0};
;     f32x16 p0, p1;
.Lc1_steady:
	v_add_u32_e32 v0, 0xc000, v191
	v_add_u32_e32 v14, 0xc000, v192
	v_add_u32_e32 v15, 0xc000, v193
	v_add_u32_e32 v171, 0xc000, v194
	v_add_u32_e32 v180, 0xc000, v195
	v_add_u32_e32 v181, 0xc000, v196
	v_add_u32_e32 v253, 0xc000, v197
	v_add_u32_e32 v254, 0xc000, v187
.Lc1_st0:
	s_add_u32 s28, s22, 0x1fe0000
	s_addc_u32 s29, s23, 0
	s_mov_b32 m0, s8
	s_nop 0
	global_load_lds_dwordx4 v146, s[22:23]
	s_addk_i32 m0, 0x400
	s_nop 0
	global_load_lds_dwordx4 v148, s[22:23]
	s_add_i32 m0, s92, 0x8000
	s_nop 0
	global_load_lds_dwordx4 v150, s[28:29]
	s_addk_i32 m0, 0x400
	s_nop 0
	global_load_lds_dwordx4 v152, s[28:29]
	v_exp_f32_e32 v80, v80
	v_exp_f32_e32 v81, v81
	v_exp_f32_e32 v82, v82
	v_exp_f32_e32 v83, v83
	v_exp_f32_e32 v84, v84
	v_exp_f32_e32 v85, v85
	v_exp_f32_e32 v86, v86
	v_exp_f32_e32 v87, v87
	v_add_f32_e32 v2, v80, v84
	v_add_f32_e32 v3, v81, v85
	v_add_f32_e32 v4, v82, v86
	v_add_f32_e32 v5, v83, v87
	v_cvt_pk_bf16_f32 v128, v80, v81
	v_cvt_pk_bf16_f32 v129, v82, v83
	v_exp_f32_e32 v88, v88
	v_exp_f32_e32 v89, v89
	v_exp_f32_e32 v90, v90
	v_exp_f32_e32 v91, v91
	v_cvt_pk_bf16_f32 v130, v84, v85
	v_cvt_pk_bf16_f32 v131, v86, v87
	v_add_f32_e32 v2, v2, v88
	v_add_f32_e32 v3, v3, v89
	v_add_f32_e32 v4, v4, v90
	v_add_f32_e32 v5, v5, v91
	v_exp_f32_e32 v92, v92
	v_exp_f32_e32 v93, v93
	v_exp_f32_e32 v94, v94
	v_exp_f32_e32 v95, v95
	v_cvt_pk_bf16_f32 v132, v88, v89
	v_cvt_pk_bf16_f32 v133, v90, v91
	v_add_f32_e32 v2, v2, v92
	v_add_f32_e32 v3, v3, v93
	v_add_f32_e32 v4, v4, v94
	v_add_f32_e32 v5, v5, v95
	v_exp_f32_e32 v96, v96
	v_exp_f32_e32 v97, v97
	v_exp_f32_e32 v98, v98
	v_exp_f32_e32 v99, v99
	v_cvt_pk_bf16_f32 v134, v92, v93
	v_cvt_pk_bf16_f32 v135, v94, v95
	v_add_f32_e32 v2, v2, v96
	v_add_f32_e32 v3, v3, v97
	v_add_f32_e32 v4, v4, v98
	v_add_f32_e32 v5, v5, v99
	v_exp_f32_e32 v100, v100
	v_exp_f32_e32 v101, v101
	v_exp_f32_e32 v102, v102
	v_exp_f32_e32 v103, v103
	v_cvt_pk_bf16_f32 v136, v96, v97
	v_cvt_pk_bf16_f32 v137, v98, v99
	v_add_f32_e32 v2, v2, v100
	v_add_f32_e32 v3, v3, v101
	v_add_f32_e32 v4, v4, v102
	v_add_f32_e32 v5, v5, v103
	v_exp_f32_e32 v104, v104
	v_exp_f32_e32 v105, v105
	v_exp_f32_e32 v106, v106
	v_exp_f32_e32 v107, v107
	v_cvt_pk_bf16_f32 v138, v100, v101
	v_cvt_pk_bf16_f32 v139, v102, v103
	v_add_f32_e32 v2, v2, v104
	v_add_f32_e32 v3, v3, v105
	v_add_f32_e32 v4, v4, v106
	v_add_f32_e32 v5, v5, v107
	v_exp_f32_e32 v108, v108
	v_exp_f32_e32 v109, v109
	v_exp_f32_e32 v110, v110
	v_exp_f32_e32 v111, v111
	v_cvt_pk_bf16_f32 v140, v104, v105
	v_cvt_pk_bf16_f32 v141, v106, v107
	v_add_f32_e32 v2, v2, v108
	v_add_f32_e32 v3, v3, v109
	v_add_f32_e32 v4, v4, v110
	v_add_f32_e32 v5, v5, v111
	v_add_f32_e32 v2, v2, v3
	v_add_f32_e32 v4, v4, v5
	v_cvt_pk_bf16_f32 v142, v108, v109
	v_add_f32_e32 v2, v2, v4
	v_cvt_pk_bf16_f32 v143, v110, v111
	v_add_f32_e32 v165, v165, v2
	ds_read_b64_tr_b16 v[2:3], v0
	ds_read_b64_tr_b16 v[4:5], v14
	ds_read_b64_tr_b16 v[6:7], v15
	ds_read_b64_tr_b16 v[8:9], v171
	ds_read_b64_tr_b16 v[10:11], v180
	ds_read_b64_tr_b16 v[12:13], v181
	ds_read_b64_tr_b16 v[172:173], v253
	ds_read_b64_tr_b16 v[174:175], v254
	ds_read_b64_tr_b16 v[198:199], v0 offset:4096
	ds_read_b64_tr_b16 v[200:201], v14 offset:4096
	ds_read_b64_tr_b16 v[202:203], v15 offset:4096
	ds_read_b64_tr_b16 v[204:205], v171 offset:4096
	ds_read_b64_tr_b16 v[206:207], v180 offset:4096
	ds_read_b64_tr_b16 v[208:209], v181 offset:4096
	s_setprio 2
	s_waitcnt lgkmcnt(12)
	v_mfma_f32_32x32x16_bf16 v[64:79], v[2:5], v[128:131], v[64:79]
	ds_read_b64_tr_b16 v[176:177], v253 offset:4096
	ds_read_b64_tr_b16 v[178:179], v254 offset:4096
	s_waitcnt lgkmcnt(12)
	v_mfma_f32_32x32x16_bf16 v[48:63], v[6:9], v[128:131], v[48:63]
	ds_read_b64_tr_b16 v[2:3], v0 offset:8192
	ds_read_b64_tr_b16 v[4:5], v14 offset:8192
	s_waitcnt lgkmcnt(12)
	v_mfma_f32_32x32x16_bf16 v[32:47], v[10:13], v[128:131], v[32:47]
	ds_read_b64_tr_b16 v[6:7], v15 offset:8192
	ds_read_b64_tr_b16 v[8:9], v171 offset:8192
	s_waitcnt lgkmcnt(12)
	v_mfma_f32_32x32x16_bf16 v[16:31], v[172:175], v[128:131], v[16:31]
	ds_read_b64_tr_b16 v[10:11], v180 offset:8192
	ds_read_b64_tr_b16 v[12:13], v181 offset:8192
	s_waitcnt lgkmcnt(12)
	v_mfma_f32_32x32x16_bf16 v[64:79], v[198:201], v[132:135], v[64:79]
	ds_read_b64_tr_b16 v[172:173], v253 offset:8192
	ds_read_b64_tr_b16 v[174:175], v254 offset:8192
	s_waitcnt lgkmcnt(12)
	v_mfma_f32_32x32x16_bf16 v[48:63], v[202:205], v[132:135], v[48:63]
	ds_read_b64_tr_b16 v[198:199], v0 offset:12288
	ds_read_b64_tr_b16 v[200:201], v14 offset:12288
	s_waitcnt lgkmcnt(12)
	v_mfma_f32_32x32x16_bf16 v[32:47], v[206:209], v[132:135], v[32:47]
	ds_read_b64_tr_b16 v[202:203], v15 offset:12288
	ds_read_b64_tr_b16 v[204:205], v171 offset:12288
	s_waitcnt lgkmcnt(12)
	v_mfma_f32_32x32x16_bf16 v[16:31], v[176:179], v[132:135], v[16:31]
	ds_read_b64_tr_b16 v[206:207], v180 offset:12288
	ds_read_b64_tr_b16 v[208:209], v181 offset:12288
	s_waitcnt lgkmcnt(12)
	v_mfma_f32_32x32x16_bf16 v[64:79], v[2:5], v[136:139], v[64:79]
	ds_read_b64_tr_b16 v[176:177], v253 offset:12288
	ds_read_b64_tr_b16 v[178:179], v254 offset:12288
	s_waitcnt lgkmcnt(12)
	v_mfma_f32_32x32x16_bf16 v[48:63], v[6:9], v[136:139], v[48:63]
	ds_read_b128 v[2:5], v145 offset:16384
	s_waitcnt lgkmcnt(11)
	v_mfma_f32_32x32x16_bf16 v[32:47], v[10:13], v[136:139], v[32:47]
	ds_read_b128 v[6:9], v145 offset:24576
	s_waitcnt lgkmcnt(10)
	v_mfma_f32_32x32x16_bf16 v[16:31], v[172:175], v[136:139], v[16:31]
	ds_read_b128 v[10:13], v159 offset:16384
	s_waitcnt lgkmcnt(9)
	v_mfma_f32_32x32x16_bf16 v[64:79], v[198:201], v[140:143], v[64:79]
	ds_read_b128 v[172:175], v159 offset:24576
	s_waitcnt lgkmcnt(8)
	v_mfma_f32_32x32x16_bf16 v[48:63], v[202:205], v[140:143], v[48:63]
	ds_read_b128 v[198:201], v160 offset:16384
	s_waitcnt lgkmcnt(7)
	v_mfma_f32_32x32x16_bf16 v[32:47], v[206:209], v[140:143], v[32:47]
	ds_read_b128 v[202:205], v160 offset:24576
	s_waitcnt lgkmcnt(6)
	v_mfma_f32_32x32x16_bf16 v[16:31], v[176:179], v[140:143], v[16:31]
	ds_read_b128 v[206:209], v161 offset:16384
	ds_read_b128 v[176:179], v161 offset:24576
	s_waitcnt lgkmcnt(7)
	v_mfma_f32_32x32x16_bf16 v[80:95], v[2:5], v[112:115], 0
	s_waitcnt lgkmcnt(6)
	v_mfma_f32_32x32x16_bf16 v[96:111], v[6:9], v[112:115], 0
	s_waitcnt lgkmcnt(5)
	v_mfma_f32_32x32x16_bf16 v[80:95], v[10:13], v[116:119], v[80:95]
	s_waitcnt lgkmcnt(4)
	v_mfma_f32_32x32x16_bf16 v[96:111], v[172:175], v[116:119], v[96:111]
	s_waitcnt lgkmcnt(3)
	v_mfma_f32_32x32x16_bf16 v[80:95], v[198:201], v[120:123], v[80:95]
	s_waitcnt lgkmcnt(2)
	v_mfma_f32_32x32x16_bf16 v[96:111], v[202:205], v[120:123], v[96:111]
	s_waitcnt lgkmcnt(1)
	v_mfma_f32_32x32x16_bf16 v[80:95], v[206:209], v[124:127], v[80:95]
	s_waitcnt lgkmcnt(0)
	v_mfma_f32_32x32x16_bf16 v[96:111], v[176:179], v[124:127], v[96:111]
	s_setprio 1
	s_waitcnt vmcnt(4)
	s_waitcnt lgkmcnt(0)
	s_barrier
; #define ATT_BAR() do { asm volatile("s_waitcnt lgkmcnt(0)" ::: "memory"); __builtin_amdgcn_s_barrier(); asm volatile("" ::: "memory"); } while (0)
; #define ATT_BASEPRIO_EARLY() do { if (comp) __builtin_amdgcn_s_setprio(1); } while (0)
; #define ATT_EVEN(j_, k2_, v1_) do { if (!F32) { if ((j_) + 2 < nt) ATT_DMAK((j_) + 2, k2_); if ((j_) + 1 < nt) ATT_DMAV((j_) + 1, v1_); } } while (0)
; template <bool F32>
; __device__ __forceinline__ void attn_unit(const AUnit& U, LAS unsigned char* lds, float lam, const float* subg) {
;     ...
;     const int mnt = active ? my_nt : 0;
;     ATT_BASEPRIO_EARLY();
;     bf16x8 pa[4];
; #pragma unroll
;     for (int k = 0; k < 4; ++k) pa[k] = (bf16x8){0, 0, 0, 0, 0, 0, 0, 0};
;     f32x16 p0, p1;
;     ...
;         for (int it = 0; it <= nt; ++it) {
;             ATT_EVEN(it, r0, r2);
;             if (it >= 1 && it <= mnt) ATT_SM(it - 1);
;             ATT_MM((it >= 1 && it <= mnt), (it < mnt), r0, r1);
;             ATT_ODD(it, r2, r1);
;             ATT_BAR();
;             { const int t_ = r0; r0 = r1; r1 = r2; r2 = t_; }
	s_add_u32 s22, s22, 0x20000
	s_addc_u32 s23, s23, 0
	s_add_i32 s95, s95, 1
	s_cmp_lt_i32 s95, s30
	s_cbranch_scc1 .Lc1_st1
	s_mov_b32 s24, 0x4000
	s_mov_b32 s93, 0x8000
	s_mov_b32 s94, 0
	s_branch .LBB0_704
.Lc1_st1:
	s_add_u32 s28, s22, 0x1fe0000
	s_addc_u32 s29, s23, 0
	s_add_i32 m0, s8, 0x4000
	s_nop 0
	global_load_lds_dwordx4 v146, s[22:23]
	s_addk_i32 m0, 0x400
	s_nop 0
	global_load_lds_dwordx4 v148, s[22:23]
	s_mov_b32 m0, s92
	s_nop 0
	global_load_lds_dwordx4 v150, s[28:29]
	s_addk_i32 m0, 0x400
	s_nop 0
	global_load_lds_dwordx4 v152, s[28:29]
	v_exp_f32_e32 v80, v80
	v_exp_f32_e32 v81, v81
	v_exp_f32_e32 v82, v82
	v_exp_f32_e32 v83, v83
	v_exp_f32_e32 v84, v84
	v_exp_f32_e32 v85, v85
	v_exp_f32_e32 v86, v86
	v_exp_f32_e32 v87, v87
	v_add_f32_e32 v2, v80, v84
	v_add_f32_e32 v3, v81, v85
	v_add_f32_e32 v4, v82, v86
	v_add_f32_e32 v5, v83, v87
	v_cvt_pk_bf16_f32 v128, v80, v81
	v_cvt_pk_bf16_f32 v129, v82, v83
	v_exp_f32_e32 v88, v88
	v_exp_f32_e32 v89, v89
	v_exp_f32_e32 v90, v90
	v_exp_f32_e32 v91, v91
	v_cvt_pk_bf16_f32 v130, v84, v85
	v_cvt_pk_bf16_f32 v131, v86, v87
	v_add_f32_e32 v2, v2, v88
	v_add_f32_e32 v3, v3, v89
	v_add_f32_e32 v4, v4, v90
	v_add_f32_e32 v5, v5, v91
	v_exp_f32_e32 v92, v92
	v_exp_f32_e32 v93, v93
	v_exp_f32_e32 v94, v94
	v_exp_f32_e32 v95, v95
	v_cvt_pk_bf16_f32 v132, v88, v89
	v_cvt_pk_bf16_f32 v133, v90, v91
	v_add_f32_e32 v2, v2, v92
	v_add_f32_e32 v3, v3, v93
	v_add_f32_e32 v4, v4, v94
	v_add_f32_e32 v5, v5, v95
	v_exp_f32_e32 v96, v96
	v_exp_f32_e32 v97, v97
	v_exp_f32_e32 v98, v98
	v_exp_f32_e32 v99, v99
	v_cvt_pk_bf16_f32 v134, v92, v93
	v_cvt_pk_bf16_f32 v135, v94, v95
	v_add_f32_e32 v2, v2, v96
	v_add_f32_e32 v3, v3, v97
	v_add_f32_e32 v4, v4, v98
	v_add_f32_e32 v5, v5, v99
	v_exp_f32_e32 v100, v100
	v_exp_f32_e32 v101, v101
	v_exp_f32_e32 v102, v102
	v_exp_f32_e32 v103, v103
	v_cvt_pk_bf16_f32 v136, v96, v97
	v_cvt_pk_bf16_f32 v137, v98, v99
	v_add_f32_e32 v2, v2, v100
	v_add_f32_e32 v3, v3, v101
	v_add_f32_e32 v4, v4, v102
	v_add_f32_e32 v5, v5, v103
	v_exp_f32_e32 v104, v104
	v_exp_f32_e32 v105, v105
	v_exp_f32_e32 v106, v106
	v_exp_f32_e32 v107, v107
	v_cvt_pk_bf16_f32 v138, v100, v101
	v_cvt_pk_bf16_f32 v139, v102, v103
	v_add_f32_e32 v2, v2, v104
	v_add_f32_e32 v3, v3, v105
	v_add_f32_e32 v4, v4, v106
	v_add_f32_e32 v5, v5, v107
	v_exp_f32_e32 v108, v108
	v_exp_f32_e32 v109, v109
	v_exp_f32_e32 v110, v110
	v_exp_f32_e32 v111, v111
	v_cvt_pk_bf16_f32 v140, v104, v105
	v_cvt_pk_bf16_f32 v141, v106, v107
	v_add_f32_e32 v2, v2, v108
	v_add_f32_e32 v3, v3, v109
	v_add_f32_e32 v4, v4, v110
	v_add_f32_e32 v5, v5, v111
	v_add_f32_e32 v2, v2, v3
	v_add_f32_e32 v4, v4, v5
	v_cvt_pk_bf16_f32 v142, v108, v109
	v_add_f32_e32 v2, v2, v4
	v_cvt_pk_bf16_f32 v143, v110, v111
	v_add_f32_e32 v165, v165, v2
	ds_read_b64_tr_b16 v[2:3], v0 offset:16384
	ds_read_b64_tr_b16 v[4:5], v14 offset:16384
	ds_read_b64_tr_b16 v[6:7], v15 offset:16384
	ds_read_b64_tr_b16 v[8:9], v171 offset:16384
	ds_read_b64_tr_b16 v[10:11], v180 offset:16384
	ds_read_b64_tr_b16 v[12:13], v181 offset:16384
	ds_read_b64_tr_b16 v[172:173], v253 offset:16384
	ds_read_b64_tr_b16 v[174:175], v254 offset:16384
	ds_read_b64_tr_b16 v[198:199], v0 offset:20480
	ds_read_b64_tr_b16 v[200:201], v14 offset:20480
	ds_read_b64_tr_b16 v[202:203], v15 offset:20480
	ds_read_b64_tr_b16 v[204:205], v171 offset:20480
	ds_read_b64_tr_b16 v[206:207], v180 offset:20480
	ds_read_b64_tr_b16 v[208:209], v181 offset:20480
	s_setprio 2
	s_waitcnt lgkmcnt(12)
	v_mfma_f32_32x32x16_bf16 v[64:79], v[2:5], v[128:131], v[64:79]
	ds_read_b64_tr_b16 v[176:177], v253 offset:20480
	ds_read_b64_tr_b16 v[178:179], v254 offset:20480
	s_waitcnt lgkmcnt(12)
	v_mfma_f32_32x32x16_bf16 v[48:63], v[6:9], v[128:131], v[48:63]
	ds_read_b64_tr_b16 v[2:3], v0 offset:24576
	ds_read_b64_tr_b16 v[4:5], v14 offset:24576
	s_waitcnt lgkmcnt(12)
	v_mfma_f32_32x32x16_bf16 v[32:47], v[10:13], v[128:131], v[32:47]
	ds_read_b64_tr_b16 v[6:7], v15 offset:24576
	ds_read_b64_tr_b16 v[8:9], v171 offset:24576
	s_waitcnt lgkmcnt(12)
	v_mfma_f32_32x32x16_bf16 v[16:31], v[172:175], v[128:131], v[16:31]
	ds_read_b64_tr_b16 v[10:11], v180 offset:24576
	ds_read_b64_tr_b16 v[12:13], v181 offset:24576
	s_waitcnt lgkmcnt(12)
	v_mfma_f32_32x32x16_bf16 v[64:79], v[198:201], v[132:135], v[64:79]
	ds_read_b64_tr_b16 v[172:173], v253 offset:24576
	ds_read_b64_tr_b16 v[174:175], v254 offset:24576
	s_waitcnt lgkmcnt(12)
	v_mfma_f32_32x32x16_bf16 v[48:63], v[202:205], v[132:135], v[48:63]
	ds_read_b64_tr_b16 v[198:199], v0 offset:28672
	ds_read_b64_tr_b16 v[200:201], v14 offset:28672
	s_waitcnt lgkmcnt(12)
	v_mfma_f32_32x32x16_bf16 v[32:47], v[206:209], v[132:135], v[32:47]
	ds_read_b64_tr_b16 v[202:203], v15 offset:28672
	ds_read_b64_tr_b16 v[204:205], v171 offset:28672
	s_waitcnt lgkmcnt(12)
	v_mfma_f32_32x32x16_bf16 v[16:31], v[176:179], v[132:135], v[16:31]
	ds_read_b64_tr_b16 v[206:207], v180 offset:28672
	ds_read_b64_tr_b16 v[208:209], v181 offset:28672
	s_waitcnt lgkmcnt(12)
	v_mfma_f32_32x32x16_bf16 v[64:79], v[2:5], v[136:139], v[64:79]
	ds_read_b64_tr_b16 v[176:177], v253 offset:28672
	ds_read_b64_tr_b16 v[178:179], v254 offset:28672
	s_waitcnt lgkmcnt(12)
	v_mfma_f32_32x32x16_bf16 v[48:63], v[6:9], v[136:139], v[48:63]
	ds_read_b128 v[2:5], v145 offset:32768
	s_waitcnt lgkmcnt(11)
	v_mfma_f32_32x32x16_bf16 v[32:47], v[10:13], v[136:139], v[32:47]
	ds_read_b128 v[6:9], v145 offset:40960
	s_waitcnt lgkmcnt(10)
	v_mfma_f32_32x32x16_bf16 v[16:31], v[172:175], v[136:139], v[16:31]
	ds_read_b128 v[10:13], v159 offset:32768
	s_waitcnt lgkmcnt(9)
	v_mfma_f32_32x32x16_bf16 v[64:79], v[198:201], v[140:143], v[64:79]
	ds_read_b128 v[172:175], v159 offset:40960
	s_waitcnt lgkmcnt(8)
	v_mfma_f32_32x32x16_bf16 v[48:63], v[202:205], v[140:143], v[48:63]
	ds_read_b128 v[198:201], v160 offset:32768
	s_waitcnt lgkmcnt(7)
	v_mfma_f32_32x32x16_bf16 v[32:47], v[206:209], v[140:143], v[32:47]
	ds_read_b128 v[202:205], v160 offset:40960
	s_waitcnt lgkmcnt(6)
	v_mfma_f32_32x32x16_bf16 v[16:31], v[176:179], v[140:143], v[16:31]
	ds_read_b128 v[206:209], v161 offset:32768
	ds_read_b128 v[176:179], v161 offset:40960
	s_waitcnt lgkmcnt(7)
	v_mfma_f32_32x32x16_bf16 v[80:95], v[2:5], v[112:115], 0
	s_waitcnt lgkmcnt(6)
	v_mfma_f32_32x32x16_bf16 v[96:111], v[6:9], v[112:115], 0
	s_waitcnt lgkmcnt(5)
	v_mfma_f32_32x32x16_bf16 v[80:95], v[10:13], v[116:119], v[80:95]
	s_waitcnt lgkmcnt(4)
	v_mfma_f32_32x32x16_bf16 v[96:111], v[172:175], v[116:119], v[96:111]
	s_waitcnt lgkmcnt(3)
	v_mfma_f32_32x32x16_bf16 v[80:95], v[198:201], v[120:123], v[80:95]
	s_waitcnt lgkmcnt(2)
	v_mfma_f32_32x32x16_bf16 v[96:111], v[202:205], v[120:123], v[96:111]
	s_waitcnt lgkmcnt(1)
	v_mfma_f32_32x32x16_bf16 v[80:95], v[206:209], v[124:127], v[80:95]
	s_waitcnt lgkmcnt(0)
	v_mfma_f32_32x32x16_bf16 v[96:111], v[176:179], v[124:127], v[96:111]
	s_setprio 1
	s_waitcnt vmcnt(4)
	s_waitcnt lgkmcnt(0)
	s_barrier
; #define ATT_BAR() do { asm volatile("s_waitcnt lgkmcnt(0)" ::: "memory"); __builtin_amdgcn_s_barrier(); asm volatile("" ::: "memory"); } while (0)
; #define ATT_EVEN(j_, k2_, v1_) do { if (!F32) { if ((j_) + 2 < nt) ATT_DMAK((j_) + 2, k2_); if ((j_) + 1 < nt) ATT_DMAV((j_) + 1, v1_); } } while (0)
; template <bool F32>
; __device__ __forceinline__ void attn_unit(const AUnit& U, LAS unsigned char* lds, float lam, const float* subg) {
;     ...
;         for (int it = 0; it <= nt; ++it) {
;             ATT_EVEN(it, r0, r2);
;             if (it >= 1 && it <= mnt) ATT_SM(it - 1);
;             ATT_MM((it >= 1 && it <= mnt), (it < mnt), r0, r1);
;             ATT_ODD(it, r2, r1);
;             ATT_BAR();
;             { const int t_ = r0; r0 = r1; r1 = r2; r2 = t_; }
	s_add_u32 s22, s22, 0x20000
	s_addc_u32 s23, s23, 0
	s_add_i32 s95, s95, 1
	s_cmp_lt_i32 s95, s30
	s_cbranch_scc1 .Lc1_st2
	s_mov_b32 s24, 0x8000
	s_mov_b32 s93, 0
	s_mov_b32 s94, 0x4000
	s_branch .LBB0_704
; #define ATT_BASEPRIO_EARLY() do { if (comp) __builtin_amdgcn_s_setprio(1); } while (0)
; template <bool F32>
; __device__ __forceinline__ void attn_unit(const AUnit& U, LAS unsigned char* lds, float lam, const float* subg) {
;     ...
;     const int mnt = active ? my_nt : 0;
;     ATT_BASEPRIO_EARLY();
;     bf16x8 pa[4];
; #pragma unroll
;     for (int k = 0; k < 4; ++k) pa[k] = (bf16x8){0, 0, 0, 0, 0, 0, 0, 0};
;     f32x16 p0, p1;
.Lc1_st2:
	s_add_u32 s28, s22, 0x1fe0000
	s_addc_u32 s29, s23, 0
	s_add_i32 m0, s8, 0x8000
	s_nop 0
	global_load_lds_dwordx4 v146, s[22:23]
	s_addk_i32 m0, 0x400
	s_nop 0
	global_load_lds_dwordx4 v148, s[22:23]
	s_add_i32 m0, s92, 0x4000
	s_nop 0
	global_load_lds_dwordx4 v150, s[28:29]
	s_addk_i32 m0, 0x400
	s_nop 0
	global_load_lds_dwordx4 v152, s[28:29]
	v_exp_f32_e32 v80, v80
	v_exp_f32_e32 v81, v81
	v_exp_f32_e32 v82, v82
	v_exp_f32_e32 v83, v83
	v_exp_f32_e32 v84, v84
	v_exp_f32_e32 v85, v85
	v_exp_f32_e32 v86, v86
	v_exp_f32_e32 v87, v87
	v_add_f32_e32 v2, v80, v84
	v_add_f32_e32 v3, v81, v85
	v_add_f32_e32 v4, v82, v86
	v_add_f32_e32 v5, v83, v87
	v_cvt_pk_bf16_f32 v128, v80, v81
	v_cvt_pk_bf16_f32 v129, v82, v83
	v_exp_f32_e32 v88, v88
	v_exp_f32_e32 v89, v89
	v_exp_f32_e32 v90, v90
	v_exp_f32_e32 v91, v91
	v_cvt_pk_bf16_f32 v130, v84, v85
	v_cvt_pk_bf16_f32 v131, v86, v87
	v_add_f32_e32 v2, v2, v88
	v_add_f32_e32 v3, v3, v89
	v_add_f32_e32 v4, v4, v90
	v_add_f32_e32 v5, v5, v91
	v_exp_f32_e32 v92, v92
	v_exp_f32_e32 v93, v93
	v_exp_f32_e32 v94, v94
	v_exp_f32_e32 v95, v95
	v_cvt_pk_bf16_f32 v132, v88, v89
	v_cvt_pk_bf16_f32 v133, v90, v91
	v_add_f32_e32 v2, v2, v92
	v_add_f32_e32 v3, v3, v93
	v_add_f32_e32 v4, v4, v94
	v_add_f32_e32 v5, v5, v95
	v_exp_f32_e32 v96, v96
	v_exp_f32_e32 v97, v97
	v_exp_f32_e32 v98, v98
	v_exp_f32_e32 v99, v99
	v_cvt_pk_bf16_f32 v134, v92, v93
	v_cvt_pk_bf16_f32 v135, v94, v95
	v_add_f32_e32 v2, v2, v96
	v_add_f32_e32 v3, v3, v97
	v_add_f32_e32 v4, v4, v98
	v_add_f32_e32 v5, v5, v99
	v_exp_f32_e32 v100, v100
	v_exp_f32_e32 v101, v101
	v_exp_f32_e32 v102, v102
	v_exp_f32_e32 v103, v103
	v_cvt_pk_bf16_f32 v136, v96, v97
	v_cvt_pk_bf16_f32 v137, v98, v99
	v_add_f32_e32 v2, v2, v100
	v_add_f32_e32 v3, v3, v101
	v_add_f32_e32 v4, v4, v102
	v_add_f32_e32 v5, v5, v103
	v_exp_f32_e32 v104, v104
	v_exp_f32_e32 v105, v105
	v_exp_f32_e32 v106, v106
	v_exp_f32_e32 v107, v107
	v_cvt_pk_bf16_f32 v138, v100, v101
	v_cvt_pk_bf16_f32 v139, v102, v103
	v_add_f32_e32 v2, v2, v104
	v_add_f32_e32 v3, v3, v105
	v_add_f32_e32 v4, v4, v106
	v_add_f32_e32 v5, v5, v107
	v_exp_f32_e32 v108, v108
	v_exp_f32_e32 v109, v109
	v_exp_f32_e32 v110, v110
	v_exp_f32_e32 v111, v111
	v_cvt_pk_bf16_f32 v140, v104, v105
	v_cvt_pk_bf16_f32 v141, v106, v107
	v_add_f32_e32 v2, v2, v108
	v_add_f32_e32 v3, v3, v109
	v_add_f32_e32 v4, v4, v110
	v_add_f32_e32 v5, v5, v111
	v_add_f32_e32 v2, v2, v3
	v_add_f32_e32 v4, v4, v5
	v_cvt_pk_bf16_f32 v142, v108, v109
	v_add_f32_e32 v2, v2, v4
	v_cvt_pk_bf16_f32 v143, v110, v111
	v_add_f32_e32 v165, v165, v2
	ds_read_b64_tr_b16 v[2:3], v0 offset:32768
	ds_read_b64_tr_b16 v[4:5], v14 offset:32768
	ds_read_b64_tr_b16 v[6:7], v15 offset:32768
	ds_read_b64_tr_b16 v[8:9], v171 offset:32768
	ds_read_b64_tr_b16 v[10:11], v180 offset:32768
	ds_read_b64_tr_b16 v[12:13], v181 offset:32768
	ds_read_b64_tr_b16 v[172:173], v253 offset:32768
	ds_read_b64_tr_b16 v[174:175], v254 offset:32768
	ds_read_b64_tr_b16 v[198:199], v0 offset:36864
	ds_read_b64_tr_b16 v[200:201], v14 offset:36864
	ds_read_b64_tr_b16 v[202:203], v15 offset:36864
	ds_read_b64_tr_b16 v[204:205], v171 offset:36864
	ds_read_b64_tr_b16 v[206:207], v180 offset:36864
	ds_read_b64_tr_b16 v[208:209], v181 offset:36864
	s_setprio 2
	s_waitcnt lgkmcnt(12)
	v_mfma_f32_32x32x16_bf16 v[64:79], v[2:5], v[128:131], v[64:79]
	ds_read_b64_tr_b16 v[176:177], v253 offset:36864
	ds_read_b64_tr_b16 v[178:179], v254 offset:36864
	s_waitcnt lgkmcnt(12)
	v_mfma_f32_32x32x16_bf16 v[48:63], v[6:9], v[128:131], v[48:63]
	ds_read_b64_tr_b16 v[2:3], v0 offset:40960
	ds_read_b64_tr_b16 v[4:5], v14 offset:40960
	s_waitcnt lgkmcnt(12)
	v_mfma_f32_32x32x16_bf16 v[32:47], v[10:13], v[128:131], v[32:47]
	ds_read_b64_tr_b16 v[6:7], v15 offset:40960
	ds_read_b64_tr_b16 v[8:9], v171 offset:40960
	s_waitcnt lgkmcnt(12)
	v_mfma_f32_32x32x16_bf16 v[16:31], v[172:175], v[128:131], v[16:31]
	ds_read_b64_tr_b16 v[10:11], v180 offset:40960
	ds_read_b64_tr_b16 v[12:13], v181 offset:40960
	s_waitcnt lgkmcnt(12)
	v_mfma_f32_32x32x16_bf16 v[64:79], v[198:201], v[132:135], v[64:79]
	ds_read_b64_tr_b16 v[172:173], v253 offset:40960
	ds_read_b64_tr_b16 v[174:175], v254 offset:40960
	s_waitcnt lgkmcnt(12)
	v_mfma_f32_32x32x16_bf16 v[48:63], v[202:205], v[132:135], v[48:63]
	ds_read_b64_tr_b16 v[198:199], v0 offset:45056
	ds_read_b64_tr_b16 v[200:201], v14 offset:45056
	s_waitcnt lgkmcnt(12)
	v_mfma_f32_32x32x16_bf16 v[32:47], v[206:209], v[132:135], v[32:47]
	ds_read_b64_tr_b16 v[202:203], v15 offset:45056
	ds_read_b64_tr_b16 v[204:205], v171 offset:45056
	s_waitcnt lgkmcnt(12)
	v_mfma_f32_32x32x16_bf16 v[16:31], v[176:179], v[132:135], v[16:31]
	ds_read_b64_tr_b16 v[206:207], v180 offset:45056
	ds_read_b64_tr_b16 v[208:209], v181 offset:45056
	s_waitcnt lgkmcnt(12)
	v_mfma_f32_32x32x16_bf16 v[64:79], v[2:5], v[136:139], v[64:79]
	ds_read_b64_tr_b16 v[176:177], v253 offset:45056
	ds_read_b64_tr_b16 v[178:179], v254 offset:45056
	s_waitcnt lgkmcnt(12)
	v_mfma_f32_32x32x16_bf16 v[48:63], v[6:9], v[136:139], v[48:63]
	ds_read_b128 v[2:5], v145
	s_waitcnt lgkmcnt(11)
	v_mfma_f32_32x32x16_bf16 v[32:47], v[10:13], v[136:139], v[32:47]
	ds_read_b128 v[6:9], v145 offset:8192
	s_waitcnt lgkmcnt(10)
	v_mfma_f32_32x32x16_bf16 v[16:31], v[172:175], v[136:139], v[16:31]
	ds_read_b128 v[10:13], v159
	s_waitcnt lgkmcnt(9)
	v_mfma_f32_32x32x16_bf16 v[64:79], v[198:201], v[140:143], v[64:79]
	ds_read_b128 v[172:175], v159 offset:8192
	s_waitcnt lgkmcnt(8)
	v_mfma_f32_32x32x16_bf16 v[48:63], v[202:205], v[140:143], v[48:63]
	ds_read_b128 v[198:201], v160
	s_waitcnt lgkmcnt(7)
	v_mfma_f32_32x32x16_bf16 v[32:47], v[206:209], v[140:143], v[32:47]
	ds_read_b128 v[202:205], v160 offset:8192
	s_waitcnt lgkmcnt(6)
	v_mfma_f32_32x32x16_bf16 v[16:31], v[176:179], v[140:143], v[16:31]
	ds_read_b128 v[206:209], v161
	ds_read_b128 v[176:179], v161 offset:8192
	s_waitcnt lgkmcnt(7)
	v_mfma_f32_32x32x16_bf16 v[80:95], v[2:5], v[112:115], 0
	s_waitcnt lgkmcnt(6)
	v_mfma_f32_32x32x16_bf16 v[96:111], v[6:9], v[112:115], 0
	s_waitcnt lgkmcnt(5)
	v_mfma_f32_32x32x16_bf16 v[80:95], v[10:13], v[116:119], v[80:95]
	s_waitcnt lgkmcnt(4)
	v_mfma_f32_32x32x16_bf16 v[96:111], v[172:175], v[116:119], v[96:111]
	s_waitcnt lgkmcnt(3)
	v_mfma_f32_32x32x16_bf16 v[80:95], v[198:201], v[120:123], v[80:95]
	s_waitcnt lgkmcnt(2)
	v_mfma_f32_32x32x16_bf16 v[96:111], v[202:205], v[120:123], v[96:111]
	s_waitcnt lgkmcnt(1)
	v_mfma_f32_32x32x16_bf16 v[80:95], v[206:209], v[124:127], v[80:95]
	s_waitcnt lgkmcnt(0)
	v_mfma_f32_32x32x16_bf16 v[96:111], v[176:179], v[124:127], v[96:111]
	s_setprio 1
	s_waitcnt vmcnt(4)
	s_waitcnt lgkmcnt(0)
	s_barrier
	s_add_u32 s22, s22, 0x20000
	s_addc_u32 s23, s23, 0
	s_add_i32 s95, s95, 1
	s_cmp_lt_i32 s95, s30
	s_cbranch_scc1 .Lc1_st0
	s_mov_b32 s24, 0
	s_mov_b32 s93, 0x4000
	s_mov_b32 s94, 0x8000
	s_branch .LBB0_704

; #define ATT_EVEN(j_, k2_, v1_) do { if (!F32) { if ((j_) + 2 < nt) ATT_DMAK((j_) + 2, k2_); if ((j_) + 1 < nt) ATT_DMAV((j_) + 1, v1_); } } while (0)
; template <bool F32>
; __device__ __forceinline__ void attn_unit(const AUnit& U, LAS unsigned char* lds, float lam, const float* subg) {
;     ...
; #pragma unroll 1
;         for (int it = 0; it <= nt; ++it) {
;             ATT_EVEN(it, r0, r2);
;             ATT_MM((it >= 1 && it <= mnt), (it < mnt), r0, r1);
.LBB0_735:
	s_cmp_lg_u32 s31, 1
	s_cbranch_scc1 .Lc0_gen
	s_cmp_lg_u32 s22, 0
	s_cbranch_scc1 .Lc0_gen
	s_min_i32 s94, s85, s87
	s_cmp_ge_i32 s31, s94
	s_cbranch_scc1 .Lc0_gen
	s_andn2_b64 vcc, exec, s[4:5]
	s_cbranch_vccz .Lc0_steady

; #define ATT_BASEPRIO_EARLY() do { if (comp) __builtin_amdgcn_s_setprio(1); } while (0)
; template <bool F32>
; __device__ __forceinline__ void attn_unit(const AUnit& U, LAS unsigned char* lds, float lam, const float* subg) {
;     ...
;     const int mnt = active ? my_nt : 0;
;     ATT_BASEPRIO_EARLY();
;     bf16x8 pa[4];
; #pragma unroll
;     for (int k = 0; k < 4; ++k) pa[k] = (bf16x8){0, 0, 0, 0, 0, 0, 0, 0};
;     f32x16 p0, p1;
.Lc0_st0:
	s_add_u32 s26, s6, 0x1fe0000
	s_addc_u32 s27, s7, 0
	s_mov_b32 m0, s8
	s_nop 0
	global_load_lds_dwordx4 v146, s[6:7]
	s_addk_i32 m0, 0x400
	s_nop 0
	global_load_lds_dwordx4 v148, s[6:7]
	s_add_i32 m0, s28, 0x8000
	s_nop 0
	global_load_lds_dwordx4 v150, s[26:27]
	s_addk_i32 m0, 0x400
	s_nop 0
	global_load_lds_dwordx4 v152, s[26:27]
	ds_read_b64_tr_b16 v[2:3], v0
	ds_read_b64_tr_b16 v[4:5], v14
	ds_read_b64_tr_b16 v[6:7], v15
	ds_read_b64_tr_b16 v[8:9], v171
	ds_read_b64_tr_b16 v[10:11], v180
	ds_read_b64_tr_b16 v[12:13], v181
	ds_read_b64_tr_b16 v[172:173], v253
	ds_read_b64_tr_b16 v[174:175], v254
	ds_read_b64_tr_b16 v[198:199], v0 offset:4096
	ds_read_b64_tr_b16 v[200:201], v14 offset:4096
	ds_read_b64_tr_b16 v[202:203], v15 offset:4096
	ds_read_b64_tr_b16 v[204:205], v171 offset:4096
	ds_read_b64_tr_b16 v[206:207], v180 offset:4096
	ds_read_b64_tr_b16 v[208:209], v181 offset:4096
	s_setprio 2
	s_waitcnt lgkmcnt(12)
	v_mfma_f32_32x32x16_bf16 v[64:79], v[2:5], v[128:131], v[64:79]
	ds_read_b64_tr_b16 v[176:177], v253 offset:4096
	ds_read_b64_tr_b16 v[178:179], v254 offset:4096
	s_waitcnt lgkmcnt(12)
	v_mfma_f32_32x32x16_bf16 v[48:63], v[6:9], v[128:131], v[48:63]
	ds_read_b64_tr_b16 v[2:3], v0 offset:8192
	ds_read_b64_tr_b16 v[4:5], v14 offset:8192
	s_waitcnt lgkmcnt(12)
	v_mfma_f32_32x32x16_bf16 v[32:47], v[10:13], v[128:131], v[32:47]
	ds_read_b64_tr_b16 v[6:7], v15 offset:8192
	ds_read_b64_tr_b16 v[8:9], v171 offset:8192
	s_waitcnt lgkmcnt(12)
	v_mfma_f32_32x32x16_bf16 v[16:31], v[172:175], v[128:131], v[16:31]
	ds_read_b64_tr_b16 v[10:11], v180 offset:8192
	ds_read_b64_tr_b16 v[12:13], v181 offset:8192
	s_waitcnt lgkmcnt(12)
	v_mfma_f32_32x32x16_bf16 v[64:79], v[198:201], v[132:135], v[64:79]
	ds_read_b64_tr_b16 v[172:173], v253 offset:8192
	ds_read_b64_tr_b16 v[174:175], v254 offset:8192
	s_waitcnt lgkmcnt(12)
	v_mfma_f32_32x32x16_bf16 v[48:63], v[202:205], v[132:135], v[48:63]
	ds_read_b64_tr_b16 v[198:199], v0 offset:12288
	ds_read_b64_tr_b16 v[200:201], v14 offset:12288
	s_waitcnt lgkmcnt(12)
	v_mfma_f32_32x32x16_bf16 v[32:47], v[206:209], v[132:135], v[32:47]
	ds_read_b64_tr_b16 v[202:203], v15 offset:12288
	ds_read_b64_tr_b16 v[204:205], v171 offset:12288
	s_waitcnt lgkmcnt(12)
	v_mfma_f32_32x32x16_bf16 v[16:31], v[176:179], v[132:135], v[16:31]
	ds_read_b64_tr_b16 v[206:207], v180 offset:12288
	ds_read_b64_tr_b16 v[208:209], v181 offset:12288
	s_waitcnt lgkmcnt(12)
	v_mfma_f32_32x32x16_bf16 v[64:79], v[2:5], v[136:139], v[64:79]
	ds_read_b64_tr_b16 v[176:177], v253 offset:12288
	ds_read_b64_tr_b16 v[178:179], v254 offset:12288
	s_waitcnt lgkmcnt(12)
	v_mfma_f32_32x32x16_bf16 v[48:63], v[6:9], v[136:139], v[48:63]
	ds_read_b128 v[2:5], v145 offset:16384
	s_waitcnt lgkmcnt(11)
	v_mfma_f32_32x32x16_bf16 v[32:47], v[10:13], v[136:139], v[32:47]
	ds_read_b128 v[6:9], v145 offset:24576
	s_waitcnt lgkmcnt(10)
	v_mfma_f32_32x32x16_bf16 v[16:31], v[172:175], v[136:139], v[16:31]
	ds_read_b128 v[10:13], v159 offset:16384
	s_waitcnt lgkmcnt(9)
	v_mfma_f32_32x32x16_bf16 v[64:79], v[198:201], v[140:143], v[64:79]
	ds_read_b128 v[172:175], v159 offset:24576
	s_waitcnt lgkmcnt(8)
	v_mfma_f32_32x32x16_bf16 v[48:63], v[202:205], v[140:143], v[48:63]
	ds_read_b128 v[198:201], v160 offset:16384
	s_waitcnt lgkmcnt(7)
	v_mfma_f32_32x32x16_bf16 v[32:47], v[206:209], v[140:143], v[32:47]
	ds_read_b128 v[202:205], v160 offset:24576
	s_waitcnt lgkmcnt(6)
	v_mfma_f32_32x32x16_bf16 v[16:31], v[176:179], v[140:143], v[16:31]
	ds_read_b128 v[206:209], v161 offset:16384
	ds_read_b128 v[176:179], v161 offset:24576
	s_waitcnt lgkmcnt(7)
	v_mfma_f32_32x32x16_bf16 v[80:95], v[2:5], v[112:115], 0
	s_waitcnt lgkmcnt(6)
	v_mfma_f32_32x32x16_bf16 v[96:111], v[6:9], v[112:115], 0
	s_waitcnt lgkmcnt(5)
	v_mfma_f32_32x32x16_bf16 v[80:95], v[10:13], v[116:119], v[80:95]
	s_waitcnt lgkmcnt(4)
	v_mfma_f32_32x32x16_bf16 v[96:111], v[172:175], v[116:119], v[96:111]
	s_waitcnt lgkmcnt(3)
	v_mfma_f32_32x32x16_bf16 v[80:95], v[198:201], v[120:123], v[80:95]
	s_waitcnt lgkmcnt(2)
	v_mfma_f32_32x32x16_bf16 v[96:111], v[202:205], v[120:123], v[96:111]
	s_waitcnt lgkmcnt(1)
	v_mfma_f32_32x32x16_bf16 v[80:95], v[206:209], v[124:127], v[80:95]
	s_waitcnt lgkmcnt(0)
	v_mfma_f32_32x32x16_bf16 v[96:111], v[176:179], v[124:127], v[96:111]
	s_setprio 0
	s_add_u32 s6, s6, 0x20000
	s_addc_u32 s7, s7, 0
	s_add_i32 s31, s31, 1
	s_nop 5
	v_exp_f32_e32 v80, v80
	v_exp_f32_e32 v81, v81
	v_exp_f32_e32 v82, v82
	v_exp_f32_e32 v83, v83
	v_exp_f32_e32 v84, v84
	v_exp_f32_e32 v85, v85
	v_exp_f32_e32 v86, v86
	v_exp_f32_e32 v87, v87
	v_add_f32_e32 v2, v80, v84
	v_add_f32_e32 v3, v81, v85
	v_add_f32_e32 v4, v82, v86
	v_add_f32_e32 v5, v83, v87
	v_cvt_pk_bf16_f32 v128, v80, v81
	v_cvt_pk_bf16_f32 v129, v82, v83
	v_exp_f32_e32 v88, v88
	v_exp_f32_e32 v89, v89
	v_exp_f32_e32 v90, v90
	v_exp_f32_e32 v91, v91
	v_cvt_pk_bf16_f32 v130, v84, v85
	v_cvt_pk_bf16_f32 v131, v86, v87
	v_add_f32_e32 v2, v2, v88
	v_add_f32_e32 v3, v3, v89
	v_add_f32_e32 v4, v4, v90
	v_add_f32_e32 v5, v5, v91
	v_exp_f32_e32 v92, v92
	v_exp_f32_e32 v93, v93
	v_exp_f32_e32 v94, v94
	v_exp_f32_e32 v95, v95
	v_cvt_pk_bf16_f32 v132, v88, v89
	v_cvt_pk_bf16_f32 v133, v90, v91
	v_add_f32_e32 v2, v2, v92
	v_add_f32_e32 v3, v3, v93
	v_add_f32_e32 v4, v4, v94
	v_add_f32_e32 v5, v5, v95
	v_exp_f32_e32 v96, v96
	v_exp_f32_e32 v97, v97
	v_exp_f32_e32 v98, v98
	v_exp_f32_e32 v99, v99
	v_cvt_pk_bf16_f32 v134, v92, v93
	v_cvt_pk_bf16_f32 v135, v94, v95
	v_add_f32_e32 v2, v2, v96
	v_add_f32_e32 v3, v3, v97
	v_add_f32_e32 v4, v4, v98
	v_add_f32_e32 v5, v5, v99
	v_exp_f32_e32 v100, v100
	v_exp_f32_e32 v101, v101
	v_exp_f32_e32 v102, v102
	v_exp_f32_e32 v103, v103
	v_cvt_pk_bf16_f32 v136, v96, v97
	v_cvt_pk_bf16_f32 v137, v98, v99
	v_add_f32_e32 v2, v2, v100
	v_add_f32_e32 v3, v3, v101
	v_add_f32_e32 v4, v4, v102
	v_add_f32_e32 v5, v5, v103
	v_exp_f32_e32 v104, v104
	v_exp_f32_e32 v105, v105
	v_exp_f32_e32 v106, v106
	v_exp_f32_e32 v107, v107
	v_cvt_pk_bf16_f32 v138, v100, v101
	v_cvt_pk_bf16_f32 v139, v102, v103
	v_add_f32_e32 v2, v2, v104
	v_add_f32_e32 v3, v3, v105
	v_add_f32_e32 v4, v4, v106
	v_add_f32_e32 v5, v5, v107
	v_exp_f32_e32 v108, v108
	v_exp_f32_e32 v109, v109
	v_exp_f32_e32 v110, v110
	v_exp_f32_e32 v111, v111
	v_cvt_pk_bf16_f32 v140, v104, v105
	v_cvt_pk_bf16_f32 v141, v106, v107
	v_add_f32_e32 v2, v2, v108
	v_add_f32_e32 v3, v3, v109
	v_add_f32_e32 v4, v4, v110
	v_add_f32_e32 v5, v5, v111
	v_add_f32_e32 v2, v2, v3
	v_add_f32_e32 v4, v4, v5
	v_cvt_pk_bf16_f32 v142, v108, v109
	v_add_f32_e32 v2, v2, v4
	v_cvt_pk_bf16_f32 v143, v110, v111
	v_add_f32_e32 v165, v165, v2
	s_waitcnt vmcnt(4)
	s_waitcnt lgkmcnt(0)
	s_barrier
	s_cmp_lt_i32 s31, s94
	s_cbranch_scc1 .Lc0_st1
	s_mov_b32 s22, 0x4000
	s_mov_b32 s29, 0x8000
	s_mov_b32 s30, 0
	s_branch .LBB0_735
; #define ATT_BASEPRIO_EARLY() do { if (comp) __builtin_amdgcn_s_setprio(1); } while (0)
; template <bool F32>
; __device__ __forceinline__ void attn_unit(const AUnit& U, LAS unsigned char* lds, float lam, const float* subg) {
;     ...
;     const int mnt = active ? my_nt : 0;
;     ATT_BASEPRIO_EARLY();
;     bf16x8 pa[4];
; #pragma unroll
;     for (int k = 0; k < 4; ++k) pa[k] = (bf16x8){0, 0, 0, 0, 0, 0, 0, 0};
;     f32x16 p0, p1;
.Lc0_st1:
	s_add_u32 s26, s6, 0x1fe0000
	s_addc_u32 s27, s7, 0
	s_add_i32 m0, s8, 0x4000
	s_nop 0
	global_load_lds_dwordx4 v146, s[6:7]
	s_addk_i32 m0, 0x400
	s_nop 0
	global_load_lds_dwordx4 v148, s[6:7]
	s_mov_b32 m0, s28
	s_nop 0
	global_load_lds_dwordx4 v150, s[26:27]
	s_addk_i32 m0, 0x400
	s_nop 0
	global_load_lds_dwordx4 v152, s[26:27]
	ds_read_b64_tr_b16 v[2:3], v0 offset:16384
	ds_read_b64_tr_b16 v[4:5], v14 offset:16384
	ds_read_b64_tr_b16 v[6:7], v15 offset:16384
	ds_read_b64_tr_b16 v[8:9], v171 offset:16384
	ds_read_b64_tr_b16 v[10:11], v180 offset:16384
	ds_read_b64_tr_b16 v[12:13], v181 offset:16384
	ds_read_b64_tr_b16 v[172:173], v253 offset:16384
	ds_read_b64_tr_b16 v[174:175], v254 offset:16384
	ds_read_b64_tr_b16 v[198:199], v0 offset:20480
	ds_read_b64_tr_b16 v[200:201], v14 offset:20480
	ds_read_b64_tr_b16 v[202:203], v15 offset:20480
	ds_read_b64_tr_b16 v[204:205], v171 offset:20480
	ds_read_b64_tr_b16 v[206:207], v180 offset:20480
	ds_read_b64_tr_b16 v[208:209], v181 offset:20480
	s_setprio 2
	s_waitcnt lgkmcnt(12)
	v_mfma_f32_32x32x16_bf16 v[64:79], v[2:5], v[128:131], v[64:79]
	ds_read_b64_tr_b16 v[176:177], v253 offset:20480
	ds_read_b64_tr_b16 v[178:179], v254 offset:20480
	s_waitcnt lgkmcnt(12)
	v_mfma_f32_32x32x16_bf16 v[48:63], v[6:9], v[128:131], v[48:63]
	ds_read_b64_tr_b16 v[2:3], v0 offset:24576
	ds_read_b64_tr_b16 v[4:5], v14 offset:24576
	s_waitcnt lgkmcnt(12)
	v_mfma_f32_32x32x16_bf16 v[32:47], v[10:13], v[128:131], v[32:47]
	ds_read_b64_tr_b16 v[6:7], v15 offset:24576
	ds_read_b64_tr_b16 v[8:9], v171 offset:24576
	s_waitcnt lgkmcnt(12)
	v_mfma_f32_32x32x16_bf16 v[16:31], v[172:175], v[128:131], v[16:31]
	ds_read_b64_tr_b16 v[10:11], v180 offset:24576
	ds_read_b64_tr_b16 v[12:13], v181 offset:24576
	s_waitcnt lgkmcnt(12)
	v_mfma_f32_32x32x16_bf16 v[64:79], v[198:201], v[132:135], v[64:79]
	ds_read_b64_tr_b16 v[172:173], v253 offset:24576
	ds_read_b64_tr_b16 v[174:175], v254 offset:24576
	s_waitcnt lgkmcnt(12)
	v_mfma_f32_32x32x16_bf16 v[48:63], v[202:205], v[132:135], v[48:63]
	ds_read_b64_tr_b16 v[198:199], v0 offset:28672
	ds_read_b64_tr_b16 v[200:201], v14 offset:28672
	s_waitcnt lgkmcnt(12)
	v_mfma_f32_32x32x16_bf16 v[32:47], v[206:209], v[132:135], v[32:47]
	ds_read_b64_tr_b16 v[202:203], v15 offset:28672
	ds_read_b64_tr_b16 v[204:205], v171 offset:28672
	s_waitcnt lgkmcnt(12)
	v_mfma_f32_32x32x16_bf16 v[16:31], v[176:179], v[132:135], v[16:31]
	ds_read_b64_tr_b16 v[206:207], v180 offset:28672
	ds_read_b64_tr_b16 v[208:209], v181 offset:28672
	s_waitcnt lgkmcnt(12)
	v_mfma_f32_32x32x16_bf16 v[64:79], v[2:5], v[136:139], v[64:79]
	ds_read_b64_tr_b16 v[176:177], v253 offset:28672
	ds_read_b64_tr_b16 v[178:179], v254 offset:28672
	s_waitcnt lgkmcnt(12)
	v_mfma_f32_32x32x16_bf16 v[48:63], v[6:9], v[136:139], v[48:63]
	ds_read_b128 v[2:5], v145 offset:32768
	s_waitcnt lgkmcnt(11)
	v_mfma_f32_32x32x16_bf16 v[32:47], v[10:13], v[136:139], v[32:47]
	ds_read_b128 v[6:9], v145 offset:40960
	s_waitcnt lgkmcnt(10)
	v_mfma_f32_32x32x16_bf16 v[16:31], v[172:175], v[136:139], v[16:31]
	ds_read_b128 v[10:13], v159 offset:32768
	s_waitcnt lgkmcnt(9)
	v_mfma_f32_32x32x16_bf16 v[64:79], v[198:201], v[140:143], v[64:79]
	ds_read_b128 v[172:175], v159 offset:40960
	s_waitcnt lgkmcnt(8)
	v_mfma_f32_32x32x16_bf16 v[48:63], v[202:205], v[140:143], v[48:63]
	ds_read_b128 v[198:201], v160 offset:32768
	s_waitcnt lgkmcnt(7)
	v_mfma_f32_32x32x16_bf16 v[32:47], v[206:209], v[140:143], v[32:47]
	ds_read_b128 v[202:205], v160 offset:40960
	s_waitcnt lgkmcnt(6)
	v_mfma_f32_32x32x16_bf16 v[16:31], v[176:179], v[140:143], v[16:31]
	ds_read_b128 v[206:209], v161 offset:32768
	ds_read_b128 v[176:179], v161 offset:40960
	s_waitcnt lgkmcnt(7)
	v_mfma_f32_32x32x16_bf16 v[80:95], v[2:5], v[112:115], 0
	s_waitcnt lgkmcnt(6)
	v_mfma_f32_32x32x16_bf16 v[96:111], v[6:9], v[112:115], 0
	s_waitcnt lgkmcnt(5)
	v_mfma_f32_32x32x16_bf16 v[80:95], v[10:13], v[116:119], v[80:95]
	s_waitcnt lgkmcnt(4)
	v_mfma_f32_32x32x16_bf16 v[96:111], v[172:175], v[116:119], v[96:111]
	s_waitcnt lgkmcnt(3)
	v_mfma_f32_32x32x16_bf16 v[80:95], v[198:201], v[120:123], v[80:95]
	s_waitcnt lgkmcnt(2)
	v_mfma_f32_32x32x16_bf16 v[96:111], v[202:205], v[120:123], v[96:111]
	s_waitcnt lgkmcnt(1)
	v_mfma_f32_32x32x16_bf16 v[80:95], v[206:209], v[124:127], v[80:95]
	s_waitcnt lgkmcnt(0)
	v_mfma_f32_32x32x16_bf16 v[96:111], v[176:179], v[124:127], v[96:111]
	s_setprio 0
	s_add_u32 s6, s6, 0x20000
	s_addc_u32 s7, s7, 0
	s_add_i32 s31, s31, 1
	s_nop 5
	v_exp_f32_e32 v80, v80
	v_exp_f32_e32 v81, v81
	v_exp_f32_e32 v82, v82
	v_exp_f32_e32 v83, v83
	v_exp_f32_e32 v84, v84
	v_exp_f32_e32 v85, v85
	v_exp_f32_e32 v86, v86
	v_exp_f32_e32 v87, v87
	v_add_f32_e32 v2, v80, v84
	v_add_f32_e32 v3, v81, v85
	v_add_f32_e32 v4, v82, v86
	v_add_f32_e32 v5, v83, v87
	v_cvt_pk_bf16_f32 v128, v80, v81
	v_cvt_pk_bf16_f32 v129, v82, v83
	v_exp_f32_e32 v88, v88
	v_exp_f32_e32 v89, v89
	v_exp_f32_e32 v90, v90
	v_exp_f32_e32 v91, v91
	v_cvt_pk_bf16_f32 v130, v84, v85
	v_cvt_pk_bf16_f32 v131, v86, v87
	v_add_f32_e32 v2, v2, v88
	v_add_f32_e32 v3, v3, v89
	v_add_f32_e32 v4, v4, v90
	v_add_f32_e32 v5, v5, v91
	v_exp_f32_e32 v92, v92
	v_exp_f32_e32 v93, v93
	v_exp_f32_e32 v94, v94
	v_exp_f32_e32 v95, v95
	v_cvt_pk_bf16_f32 v132, v88, v89
	v_cvt_pk_bf16_f32 v133, v90, v91
	v_add_f32_e32 v2, v2, v92
	v_add_f32_e32 v3, v3, v93
	v_add_f32_e32 v4, v4, v94
	v_add_f32_e32 v5, v5, v95
	v_exp_f32_e32 v96, v96
	v_exp_f32_e32 v97, v97
	v_exp_f32_e32 v98, v98
	v_exp_f32_e32 v99, v99
	v_cvt_pk_bf16_f32 v134, v92, v93
	v_cvt_pk_bf16_f32 v135, v94, v95
	v_add_f32_e32 v2, v2, v96
	v_add_f32_e32 v3, v3, v97
	v_add_f32_e32 v4, v4, v98
	v_add_f32_e32 v5, v5, v99
	v_exp_f32_e32 v100, v100
	v_exp_f32_e32 v101, v101
	v_exp_f32_e32 v102, v102
	v_exp_f32_e32 v103, v103
	v_cvt_pk_bf16_f32 v136, v96, v97
	v_cvt_pk_bf16_f32 v137, v98, v99
	v_add_f32_e32 v2, v2, v100
	v_add_f32_e32 v3, v3, v101
	v_add_f32_e32 v4, v4, v102
	v_add_f32_e32 v5, v5, v103
	v_exp_f32_e32 v104, v104
	v_exp_f32_e32 v105, v105
	v_exp_f32_e32 v106, v106
	v_exp_f32_e32 v107, v107
	v_cvt_pk_bf16_f32 v138, v100, v101
	v_cvt_pk_bf16_f32 v139, v102, v103
	v_add_f32_e32 v2, v2, v104
	v_add_f32_e32 v3, v3, v105
	v_add_f32_e32 v4, v4, v106
	v_add_f32_e32 v5, v5, v107
	v_exp_f32_e32 v108, v108
	v_exp_f32_e32 v109, v109
	v_exp_f32_e32 v110, v110
	v_exp_f32_e32 v111, v111
	v_cvt_pk_bf16_f32 v140, v104, v105
	v_cvt_pk_bf16_f32 v141, v106, v107
	v_add_f32_e32 v2, v2, v108
	v_add_f32_e32 v3, v3, v109
	v_add_f32_e32 v4, v4, v110
	v_add_f32_e32 v5, v5, v111
	v_add_f32_e32 v2, v2, v3
	v_add_f32_e32 v4, v4, v5
	v_cvt_pk_bf16_f32 v142, v108, v109
	v_add_f32_e32 v2, v2, v4
	v_cvt_pk_bf16_f32 v143, v110, v111
	v_add_f32_e32 v165, v165, v2
	s_waitcnt vmcnt(4)
	s_waitcnt lgkmcnt(0)
	s_barrier
	s_cmp_lt_i32 s31, s94
	s_cbranch_scc1 .Lc0_st2
	s_mov_b32 s22, 0x8000
	s_mov_b32 s29, 0
	s_mov_b32 s30, 0x4000
	s_branch .LBB0_735
; #define ATT_BASEPRIO_EARLY() do { if (comp) __builtin_amdgcn_s_setprio(1); } while (0)
; template <bool F32>
; __device__ __forceinline__ void attn_unit(const AUnit& U, LAS unsigned char* lds, float lam, const float* subg) {
;     ...
;     const int mnt = active ? my_nt : 0;
;     ATT_BASEPRIO_EARLY();
;     bf16x8 pa[4];
; #pragma unroll
;     for (int k = 0; k < 4; ++k) pa[k] = (bf16x8){0, 0, 0, 0, 0, 0, 0, 0};
;     f32x16 p0, p1;
.Lc0_st2:
	s_add_u32 s26, s6, 0x1fe0000
	s_addc_u32 s27, s7, 0
	s_add_i32 m0, s8, 0x8000
	s_nop 0
	global_load_lds_dwordx4 v146, s[6:7]
	s_addk_i32 m0, 0x400
	s_nop 0
	global_load_lds_dwordx4 v148, s[6:7]
	s_add_i32 m0, s28, 0x4000
	s_nop 0
	global_load_lds_dwordx4 v150, s[26:27]
	s_addk_i32 m0, 0x400
	s_nop 0
	global_load_lds_dwordx4 v152, s[26:27]
	ds_read_b64_tr_b16 v[2:3], v0 offset:32768
	ds_read_b64_tr_b16 v[4:5], v14 offset:32768
	ds_read_b64_tr_b16 v[6:7], v15 offset:32768
	ds_read_b64_tr_b16 v[8:9], v171 offset:32768
	ds_read_b64_tr_b16 v[10:11], v180 offset:32768
	ds_read_b64_tr_b16 v[12:13], v181 offset:32768
	ds_read_b64_tr_b16 v[172:173], v253 offset:32768
	ds_read_b64_tr_b16 v[174:175], v254 offset:32768
	ds_read_b64_tr_b16 v[198:199], v0 offset:36864
	ds_read_b64_tr_b16 v[200:201], v14 offset:36864
	ds_read_b64_tr_b16 v[202:203], v15 offset:36864
	ds_read_b64_tr_b16 v[204:205], v171 offset:36864
	ds_read_b64_tr_b16 v[206:207], v180 offset:36864
	ds_read_b64_tr_b16 v[208:209], v181 offset:36864
	s_setprio 2
	s_waitcnt lgkmcnt(12)
	v_mfma_f32_32x32x16_bf16 v[64:79], v[2:5], v[128:131], v[64:79]
	ds_read_b64_tr_b16 v[176:177], v253 offset:36864
	ds_read_b64_tr_b16 v[178:179], v254 offset:36864
	s_waitcnt lgkmcnt(12)
	v_mfma_f32_32x32x16_bf16 v[48:63], v[6:9], v[128:131], v[48:63]
	ds_read_b64_tr_b16 v[2:3], v0 offset:40960
	ds_read_b64_tr_b16 v[4:5], v14 offset:40960
	s_waitcnt lgkmcnt(12)
	v_mfma_f32_32x32x16_bf16 v[32:47], v[10:13], v[128:131], v[32:47]
	ds_read_b64_tr_b16 v[6:7], v15 offset:40960
	ds_read_b64_tr_b16 v[8:9], v171 offset:40960
	s_waitcnt lgkmcnt(12)
	v_mfma_f32_32x32x16_bf16 v[16:31], v[172:175], v[128:131], v[16:31]
	ds_read_b64_tr_b16 v[10:11], v180 offset:40960
	ds_read_b64_tr_b16 v[12:13], v181 offset:40960
	s_waitcnt lgkmcnt(12)
	v_mfma_f32_32x32x16_bf16 v[64:79], v[198:201], v[132:135], v[64:79]
	ds_read_b64_tr_b16 v[172:173], v253 offset:40960
	ds_read_b64_tr_b16 v[174:175], v254 offset:40960
	s_waitcnt lgkmcnt(12)
	v_mfma_f32_32x32x16_bf16 v[48:63], v[202:205], v[132:135], v[48:63]
	ds_read_b64_tr_b16 v[198:199], v0 offset:45056
	ds_read_b64_tr_b16 v[200:201], v14 offset:45056
	s_waitcnt lgkmcnt(12)
	v_mfma_f32_32x32x16_bf16 v[32:47], v[206:209], v[132:135], v[32:47]
	ds_read_b64_tr_b16 v[202:203], v15 offset:45056
	ds_read_b64_tr_b16 v[204:205], v171 offset:45056
	s_waitcnt lgkmcnt(12)
	v_mfma_f32_32x32x16_bf16 v[16:31], v[176:179], v[132:135], v[16:31]
	ds_read_b64_tr_b16 v[206:207], v180 offset:45056
	ds_read_b64_tr_b16 v[208:209], v181 offset:45056
	s_waitcnt lgkmcnt(12)
	v_mfma_f32_32x32x16_bf16 v[64:79], v[2:5], v[136:139], v[64:79]
	ds_read_b64_tr_b16 v[176:177], v253 offset:45056
	ds_read_b64_tr_b16 v[178:179], v254 offset:45056
	s_waitcnt lgkmcnt(12)
	v_mfma_f32_32x32x16_bf16 v[48:63], v[6:9], v[136:139], v[48:63]
	ds_read_b128 v[2:5], v145
	s_waitcnt lgkmcnt(11)
	v_mfma_f32_32x32x16_bf16 v[32:47], v[10:13], v[136:139], v[32:47]
	ds_read_b128 v[6:9], v145 offset:8192
	s_waitcnt lgkmcnt(10)
	v_mfma_f32_32x32x16_bf16 v[16:31], v[172:175], v[136:139], v[16:31]
	ds_read_b128 v[10:13], v159
	s_waitcnt lgkmcnt(9)
	v_mfma_f32_32x32x16_bf16 v[64:79], v[198:201], v[140:143], v[64:79]
	ds_read_b128 v[172:175], v159 offset:8192
	s_waitcnt lgkmcnt(8)
	v_mfma_f32_32x32x16_bf16 v[48:63], v[202:205], v[140:143], v[48:63]
	ds_read_b128 v[198:201], v160
	s_waitcnt lgkmcnt(7)
	v_mfma_f32_32x32x16_bf16 v[32:47], v[206:209], v[140:143], v[32:47]
	ds_read_b128 v[202:205], v160 offset:8192
	s_waitcnt lgkmcnt(6)
	v_mfma_f32_32x32x16_bf16 v[16:31], v[176:179], v[140:143], v[16:31]
	ds_read_b128 v[206:209], v161
	ds_read_b128 v[176:179], v161 offset:8192
	s_waitcnt lgkmcnt(7)
	v_mfma_f32_32x32x16_bf16 v[80:95], v[2:5], v[112:115], 0
	s_waitcnt lgkmcnt(6)
	v_mfma_f32_32x32x16_bf16 v[96:111], v[6:9], v[112:115], 0
	s_waitcnt lgkmcnt(5)
	v_mfma_f32_32x32x16_bf16 v[80:95], v[10:13], v[116:119], v[80:95]
	s_waitcnt lgkmcnt(4)
	v_mfma_f32_32x32x16_bf16 v[96:111], v[172:175], v[116:119], v[96:111]
	s_waitcnt lgkmcnt(3)
	v_mfma_f32_32x32x16_bf16 v[80:95], v[198:201], v[120:123], v[80:95]
	s_waitcnt lgkmcnt(2)
	v_mfma_f32_32x32x16_bf16 v[96:111], v[202:205], v[120:123], v[96:111]
	s_waitcnt lgkmcnt(1)
	v_mfma_f32_32x32x16_bf16 v[80:95], v[206:209], v[124:127], v[80:95]
	s_waitcnt lgkmcnt(0)
	v_mfma_f32_32x32x16_bf16 v[96:111], v[176:179], v[124:127], v[96:111]
	s_setprio 0
	s_add_u32 s6, s6, 0x20000
	s_addc_u32 s7, s7, 0
	s_add_i32 s31, s31, 1
	s_nop 5
	v_exp_f32_e32 v80, v80
	v_exp_f32_e32 v81, v81
	v_exp_f32_e32 v82, v82
	v_exp_f32_e32 v83, v83
	v_exp_f32_e32 v84, v84
	v_exp_f32_e32 v85, v85
	v_exp_f32_e32 v86, v86
	v_exp_f32_e32 v87, v87
	v_add_f32_e32 v2, v80, v84
	v_add_f32_e32 v3, v81, v85
	v_add_f32_e32 v4, v82, v86
	v_add_f32_e32 v5, v83, v87
	v_cvt_pk_bf16_f32 v128, v80, v81
	v_cvt_pk_bf16_f32 v129, v82, v83
	v_exp_f32_e32 v88, v88
	v_exp_f32_e32 v89, v89
	v_exp_f32_e32 v90, v90
	v_exp_f32_e32 v91, v91
	v_cvt_pk_bf16_f32 v130, v84, v85
	v_cvt_pk_bf16_f32 v131, v86, v87
	v_add_f32_e32 v2, v2, v88
	v_add_f32_e32 v3, v3, v89
	v_add_f32_e32 v4, v4, v90
	v_add_f32_e32 v5, v5, v91
	v_exp_f32_e32 v92, v92
	v_exp_f32_e32 v93, v93
	v_exp_f32_e32 v94, v94
	v_exp_f32_e32 v95, v95
	v_cvt_pk_bf16_f32 v132, v88, v89
	v_cvt_pk_bf16_f32 v133, v90, v91
	v_add_f32_e32 v2, v2, v92
	v_add_f32_e32 v3, v3, v93
	v_add_f32_e32 v4, v4, v94
	v_add_f32_e32 v5, v5, v95
	v_exp_f32_e32 v96, v96
	v_exp_f32_e32 v97, v97
	v_exp_f32_e32 v98, v98
	v_exp_f32_e32 v99, v99
	v_cvt_pk_bf16_f32 v134, v92, v93
	v_cvt_pk_bf16_f32 v135, v94, v95
	v_add_f32_e32 v2, v2, v96
	v_add_f32_e32 v3, v3, v97
	v_add_f32_e32 v4, v4, v98
	v_add_f32_e32 v5, v5, v99
	v_exp_f32_e32 v100, v100
	v_exp_f32_e32 v101, v101
	v_exp_f32_e32 v102, v102
	v_exp_f32_e32 v103, v103
	v_cvt_pk_bf16_f32 v136, v96, v97
	v_cvt_pk_bf16_f32 v137, v98, v99
	v_add_f32_e32 v2, v2, v100
	v_add_f32_e32 v3, v3, v101
	v_add_f32_e32 v4, v4, v102
	v_add_f32_e32 v5, v5, v103
	v_exp_f32_e32 v104, v104
	v_exp_f32_e32 v105, v105
	v_exp_f32_e32 v106, v106
	v_exp_f32_e32 v107, v107
	v_cvt_pk_bf16_f32 v138, v100, v101
	v_cvt_pk_bf16_f32 v139, v102, v103
	v_add_f32_e32 v2, v2, v104
	v_add_f32_e32 v3, v3, v105
	v_add_f32_e32 v4, v4, v106
	v_add_f32_e32 v5, v5, v107
	v_exp_f32_e32 v108, v108
	v_exp_f32_e32 v109, v109
	v_exp_f32_e32 v110, v110
	v_exp_f32_e32 v111, v111
	v_cvt_pk_bf16_f32 v140, v104, v105
	v_cvt_pk_bf16_f32 v141, v106, v107
	v_add_f32_e32 v2, v2, v108
	v_add_f32_e32 v3, v3, v109
	v_add_f32_e32 v4, v4, v110
	v_add_f32_e32 v5, v5, v111
	v_add_f32_e32 v2, v2, v3
	v_add_f32_e32 v4, v4, v5
	v_cvt_pk_bf16_f32 v142, v108, v109
	v_add_f32_e32 v2, v2, v4
	v_cvt_pk_bf16_f32 v143, v110, v111
	v_add_f32_e32 v165, v165, v2
	s_waitcnt vmcnt(4)
	s_waitcnt lgkmcnt(0)
	s_barrier
	s_cmp_lt_i32 s31, s94
	s_cbranch_scc1 .Lc0_st0
	s_mov_b32 s22, 0
	s_mov_b32 s29, 0x4000
	s_mov_b32 s30, 0x8000
	s_branch .LBB0_735
